# hyena alias fix: serial per-lane LDS loops replaced by a wave-0 lane-parallel precompute (same fma order, bit-identical) + 4 ds_read_b128 in the output loop
# speedup vs baseline: 1.0896x; 1.0896x over previous
; template <int L, int N, int NB> DEVQ void hyena_item(const Params& P, LAS unsigned char* lds, bf16* pT, float* zs, int d, size_t m0, const cf* specd, const float* cornerd) {
;     ...
;         const float skv = P.in[17][o * 1024 + d];
;         const int gc = (o + 1) * 1024 + d;
;         const float w0 = cw[gc], w1 = cw[3072 + gc], w2 = cw[6144 + gc], bs = cb[gc];
;     ...
;                 if (t0 < 16 || t0 + 7 > N / 2) {
; #pragma unroll
;                     for (int e = 0; e < 8; ++e) { const int t = t0 + e;
;                         if (t > N / 2) { const int n1 = t - N / 2 - 1; for (int s = 0; s <= n1; ++s) { const float c = cf1[n1 - s]; ya[e] += c * cxb[s]; yb[e] += c * cxb[32 + s]; } }
;                         if (t < 16) { for (int k = 0; k <= 15 - t; ++k) { const float c = cf2[k]; ya[e] += c * cxb[16 + t + k]; yb[e] += c * cxb[48 + t + k]; } } } }
.LBB0_274:
	s_or_b64 exec, exec, s[0:1]
	s_lshl_b32 s0, s90, 10
	s_add_i32 s0, s0, s22
	s_ashr_i32 s1, s0, 31
	s_lshl_b64 s[2:3], s[0:1], 2
	s_add_u32 s2, s17, s2
	s_addc_u32 s3, s16, s3
	s_addk_i32 s0, 0x400
	s_ashr_i32 s1, s0, 31
	v_mov_b64_e32 v[0:1], s[2:3]
	s_lshl_b64 s[2:3], s[0:1], 2
	s_add_u32 s4, s27, s2
	s_addc_u32 s5, s25, s3
	v_mov_b32_e32 v4, s4
	v_mov_b32_e32 v5, s5
	v_add_co_u32_e32 v2, vcc, s53, v4
	s_movk_i32 s1, 0x6000
	s_nop 0
	v_addc_co_u32_e32 v3, vcc, 0, v5, vcc
	s_add_u32 s2, s67, s2
	s_waitcnt lgkmcnt(0)
	s_barrier
	s_waitcnt vmcnt(0)
	flat_load_dword v42, v[0:1]
	v_mov_b64_e32 v[0:1], s[4:5]
	v_add_co_u32_e32 v4, vcc, s1, v4
	s_addc_u32 s3, s66, s3
	s_nop 0
	v_addc_co_u32_e32 v5, vcc, 0, v5, vcc
	flat_load_dword v44, v[0:1]
	flat_load_dword v46, v[2:3]
	flat_load_dword v48, v[4:5]
	v_mov_b64_e32 v[0:1], s[2:3]
	flat_load_dword v50, v[0:1]
	v_readfirstlane_b32 s28, v61
	s_lshl_b32 s29, s90, 7
	s_nop 3
	s_cmp_lt_u32 s28, 64
	s_cbranch_scc0 .Lfixpre_skip_lp
	v_and_b32_e32 v0, 31, v61
	v_bfe_u32 v1, v61, 5, 1
	v_cmp_gt_u32_e64 s[94:95], 16, v0
	v_add_u32_e32 v2, -16, v0
	v_sub_u32_e32 v3, 16, v0
	v_add_u32_e32 v4, 16, v0
	v_lshlrev_b32_e32 v5, 2, v2
	v_cndmask_b32_e64 v3, v2, v3, s[94:95]
	v_cndmask_b32_e64 v4, 0, v4, s[94:95]
	v_add_u32_e32 v5, -4, v5
	v_lshl_add_u32 v4, v1, 5, v4
	v_cndmask_b32_e64 v5, v5, 64, s[94:95]
	v_lshlrev_b32_e32 v4, 2, v4
	v_add_u32_e32 v5, s29, v5
	v_add_u32_e32 v4, 0x20000, v4
	v_add_u32_e32 v5, 0x20200, v5
	v_cndmask_b32_e64 v6, -4, 4, s[94:95]
	v_add_u32_e32 v7, 0x1000, v2
	v_cndmask_b32_e64 v7, v7, v0, s[94:95]
	v_lshlrev_b32_e32 v7, 4, v7
	v_lshl_add_u32 v7, v1, 2, v7
	v_lshl_add_u32 v1, v61, 2, 0
	v_add_u32_e32 v1, 0x20800, v1
	v_mad_i32_i24 v0, v6, 0, v5
	ds_read_b32 v24, v0
	v_mad_i32_i24 v0, v6, 1, v5
	ds_read_b32 v25, v0
	v_mad_i32_i24 v0, v6, 2, v5
	ds_read_b32 v26, v0
	v_mad_i32_i24 v0, v6, 3, v5
	ds_read_b32 v27, v0
	v_mad_i32_i24 v0, v6, 4, v5
	ds_read_b32 v28, v0
	v_mad_i32_i24 v0, v6, 5, v5
	ds_read_b32 v29, v0
	v_mad_i32_i24 v0, v6, 6, v5
	ds_read_b32 v30, v0
	v_mad_i32_i24 v0, v6, 7, v5
	ds_read_b32 v31, v0
	v_mad_i32_i24 v0, v6, 8, v5
	ds_read_b32 v32, v0
	v_mad_i32_i24 v0, v6, 9, v5
	ds_read_b32 v33, v0
	v_mad_i32_i24 v0, v6, 10, v5
	ds_read_b32 v34, v0
	v_mad_i32_i24 v0, v6, 11, v5
	ds_read_b32 v35, v0
	v_mad_i32_i24 v0, v6, 12, v5
	ds_read_b32 v36, v0
	v_mad_i32_i24 v0, v6, 13, v5
	ds_read_b32 v37, v0
	v_mad_i32_i24 v0, v6, 14, v5
	ds_read_b32 v38, v0
	v_mad_i32_i24 v0, v6, 15, v5
	ds_read_b32 v39, v0
	ds_read_b32 v2, v7
	ds_read_b32 v8, v4
	ds_read_b32 v9, v4 offset:4
	ds_read_b32 v10, v4 offset:8
	ds_read_b32 v11, v4 offset:12
	ds_read_b32 v12, v4 offset:16
	ds_read_b32 v13, v4 offset:20
	ds_read_b32 v14, v4 offset:24
	ds_read_b32 v15, v4 offset:28
	ds_read_b32 v16, v4 offset:32
	ds_read_b32 v17, v4 offset:36
	ds_read_b32 v18, v4 offset:40
	ds_read_b32 v19, v4 offset:44
	ds_read_b32 v20, v4 offset:48
	ds_read_b32 v21, v4 offset:52
	ds_read_b32 v22, v4 offset:56
	ds_read_b32 v23, v4 offset:60
	s_waitcnt lgkmcnt(0)
	v_cmpx_gt_u32_e64 s[96:97], v3, 0
	v_fmac_f32_e32 v2, v24, v8
	v_cmpx_gt_u32_e64 s[96:97], v3, 1
	v_fmac_f32_e32 v2, v25, v9
	v_cmpx_gt_u32_e64 s[96:97], v3, 2
	v_fmac_f32_e32 v2, v26, v10
	v_cmpx_gt_u32_e64 s[96:97], v3, 3
	v_fmac_f32_e32 v2, v27, v11
	v_cmpx_gt_u32_e64 s[96:97], v3, 4
	v_fmac_f32_e32 v2, v28, v12
	v_cmpx_gt_u32_e64 s[96:97], v3, 5
	v_fmac_f32_e32 v2, v29, v13
	v_cmpx_gt_u32_e64 s[96:97], v3, 6
	v_fmac_f32_e32 v2, v30, v14
	v_cmpx_gt_u32_e64 s[96:97], v3, 7
	v_fmac_f32_e32 v2, v31, v15
	v_cmpx_gt_u32_e64 s[96:97], v3, 8
	v_fmac_f32_e32 v2, v32, v16
	v_cmpx_gt_u32_e64 s[96:97], v3, 9
	v_fmac_f32_e32 v2, v33, v17
	v_cmpx_gt_u32_e64 s[96:97], v3, 10
	v_fmac_f32_e32 v2, v34, v18
	v_cmpx_gt_u32_e64 s[96:97], v3, 11
	v_fmac_f32_e32 v2, v35, v19
	v_cmpx_gt_u32_e64 s[96:97], v3, 12
	v_fmac_f32_e32 v2, v36, v20
	v_cmpx_gt_u32_e64 s[96:97], v3, 13
	v_fmac_f32_e32 v2, v37, v21
	v_cmpx_gt_u32_e64 s[96:97], v3, 14
	v_fmac_f32_e32 v2, v38, v22
	v_cmpx_gt_u32_e64 s[96:97], v3, 15
	v_fmac_f32_e32 v2, v39, v23
	s_mov_b64 exec, -1
	ds_write_b32 v1, v2
	ds_read_b32 v2, v7 offset:8
	ds_read_b32 v8, v4 offset:256
	ds_read_b32 v9, v4 offset:260
	ds_read_b32 v10, v4 offset:264
	ds_read_b32 v11, v4 offset:268
	ds_read_b32 v12, v4 offset:272
	ds_read_b32 v13, v4 offset:276
	ds_read_b32 v14, v4 offset:280
	ds_read_b32 v15, v4 offset:284
	ds_read_b32 v16, v4 offset:288
	ds_read_b32 v17, v4 offset:292
	ds_read_b32 v18, v4 offset:296
	ds_read_b32 v19, v4 offset:300
	ds_read_b32 v20, v4 offset:304
	ds_read_b32 v21, v4 offset:308
	ds_read_b32 v22, v4 offset:312
	ds_read_b32 v23, v4 offset:316
	s_waitcnt lgkmcnt(0)
	v_cmpx_gt_u32_e64 s[96:97], v3, 0
	v_fmac_f32_e32 v2, v24, v8
	v_cmpx_gt_u32_e64 s[96:97], v3, 1
	v_fmac_f32_e32 v2, v25, v9
	v_cmpx_gt_u32_e64 s[96:97], v3, 2
	v_fmac_f32_e32 v2, v26, v10
	v_cmpx_gt_u32_e64 s[96:97], v3, 3
	v_fmac_f32_e32 v2, v27, v11
	v_cmpx_gt_u32_e64 s[96:97], v3, 4
	v_fmac_f32_e32 v2, v28, v12
	v_cmpx_gt_u32_e64 s[96:97], v3, 5
	v_fmac_f32_e32 v2, v29, v13
	v_cmpx_gt_u32_e64 s[96:97], v3, 6
	v_fmac_f32_e32 v2, v30, v14
	v_cmpx_gt_u32_e64 s[96:97], v3, 7
	v_fmac_f32_e32 v2, v31, v15
	v_cmpx_gt_u32_e64 s[96:97], v3, 8
	v_fmac_f32_e32 v2, v32, v16
	v_cmpx_gt_u32_e64 s[96:97], v3, 9
	v_fmac_f32_e32 v2, v33, v17
	v_cmpx_gt_u32_e64 s[96:97], v3, 10
	v_fmac_f32_e32 v2, v34, v18
	v_cmpx_gt_u32_e64 s[96:97], v3, 11
	v_fmac_f32_e32 v2, v35, v19
	v_cmpx_gt_u32_e64 s[96:97], v3, 12
	v_fmac_f32_e32 v2, v36, v20
	v_cmpx_gt_u32_e64 s[96:97], v3, 13
	v_fmac_f32_e32 v2, v37, v21
	v_cmpx_gt_u32_e64 s[96:97], v3, 14
	v_fmac_f32_e32 v2, v38, v22
	v_cmpx_gt_u32_e64 s[96:97], v3, 15
	v_fmac_f32_e32 v2, v39, v23
	s_mov_b64 exec, -1
	ds_write_b32 v1, v2 offset:256
	s_waitcnt lgkmcnt(0)
; #define LAS __attribute__((address_space(3)))
; template <int L, int N, int NB> DEVQ void hyena_item(const Params& P, LAS unsigned char* lds, bf16* pT, float* zs, int d, size_t m0, const cf* specd, const float* cornerd) {
;     ...
; #pragma unroll
;         for (int nb = 0; nb < NB; ++nb) {
;             bf16* pv = pT + (size_t)d * TPAD + m0 + (size_t)nb * 2 * L; const bf16* pg = pT + (size_t)gc * TPAD + m0 + (size_t)nb * 2 * L;
;             float* zb = zs + nb * 2 * L; LAS cf* Xb = X + nb; const LAS float* cxb = cx + 64 * nb;
; #pragma unroll 1
;             for (int q = tid; q < NG; q += NTHR) { const int t0 = 8 * q;
;                 float ga[8], gb[8], ya[8], yb[8];
;                 sconv8(pg, t0, L, w0, w1, w2, bs, ga); sconv8(pg + L, t0, L, w0, w1, w2, bs, gb);
.Lfixpre_skip_lp:
	s_lshl_b32 s2, s90, 7
	s_mul_hi_i32 s1, s0, 0x28400
	s_mul_i32 s0, s0, 0x28400
	s_add_u32 s84, s23, s0
	s_movk_i32 s0, 0x202
	v_lshlrev_b32_e32 v40, 3, v61
	v_lshlrev_b32_e32 v101, 5, v61
	s_addc_u32 s85, s59, s1
	v_cmp_gt_i32_e64 s[4:5], s0, v61
	v_add_u32_e32 v41, 0xfffff000, v40
	v_sub_u32_e32 v86, 15, v40
	v_add_u32_e32 v102, s2, v101
	v_add_u32_e32 v87, 0xfffff001, v40
	v_sub_u32_e32 v88, 14, v40
	v_add_u32_e32 v89, 0xfffff002, v40
	v_sub_u32_e32 v90, 13, v40
	v_add_u32_e32 v91, 0xfffff003, v40
	v_sub_u32_e32 v92, 12, v40
	v_add_u32_e32 v93, 0xfffff004, v40
	v_sub_u32_e32 v94, 11, v40
	v_add_u32_e32 v95, 0xfffff005, v40
	v_sub_u32_e32 v96, 10, v40
	v_add_u32_e32 v97, 0xfffff006, v40
	v_sub_u32_e32 v98, 9, v40
	v_add_u32_e32 v99, 0xfffff007, v40
	v_sub_u32_e32 v100, 8, v40
	s_and_saveexec_b64 s[86:87], s[4:5]
	s_movk_i32 s55, 0x200
	s_cbranch_execz .LBB0_355
	v_readlane_b32 s0, v253, 10
	s_add_u32 s88, s84, 0x2020
	s_addc_u32 s89, s85, 0
	v_add_u32_e32 v103, s0, v102
	v_readlane_b32 s0, v254, 37
	s_add_i32 s3, s2, 0
	s_waitcnt vmcnt(0) lgkmcnt(0)
	v_mov_b32_e32 v51, v50
	v_add_u32_e32 v104, s0, v101
	v_readlane_b32 s0, v253, 11
	v_mov_b32_e32 v49, v48
	v_mov_b32_e32 v45, v44
	v_add_u32_e32 v105, s0, v102
	v_readlane_b32 s0, v253, 12
	v_mov_b32_e32 v47, v46
	v_mov_b32_e32 v43, v42
	v_add_u32_e32 v107, s0, v101
	v_readlane_b32 s0, v253, 13
	v_mov_b32_e32 v52, v46
	v_mov_b32_e32 v53, v44
	v_add_u32_e32 v109, s0, v102
	v_readlane_b32 s0, v253, 14
	s_add_i32 s3, s3, 0x20240
	v_add_u32_e32 v106, 0xfffff001, v40
	v_add_u32_e32 v111, s0, v101
	v_readlane_b32 s0, v253, 15
	v_sub_u32_e32 v108, 14, v40
	v_add_u32_e32 v110, 0xfffff002, v40
	v_add_u32_e32 v113, s0, v102
	v_readlane_b32 s0, v253, 16
	v_sub_u32_e32 v112, 13, v40
	v_add_u32_e32 v114, 0xfffff003, v40
	v_add_u32_e32 v115, s0, v101
	v_readlane_b32 s0, v253, 17
	v_sub_u32_e32 v116, 12, v40
	v_add_u32_e32 v118, 0xfffff004, v40
	v_add_u32_e32 v117, s0, v102
	v_readlane_b32 s0, v254, 38
	v_sub_u32_e32 v120, 11, v40
	v_add_u32_e32 v122, 0xfffff005, v40
	v_add_u32_e32 v119, s0, v101
	v_readlane_b32 s0, v253, 18
	v_sub_u32_e32 v124, 10, v40
	v_add_u32_e32 v126, 0xfffff006, v40
	v_add_u32_e32 v121, s0, v102
	v_readlane_b32 s0, v253, 19
	v_sub_u32_e32 v128, 9, v40
	v_add_u32_e32 v133, 0xfffff007, v40
	v_add_u32_e32 v123, s0, v101
	v_readlane_b32 s0, v253, 20
	v_sub_u32_e32 v138, 8, v40
	s_mov_b64 s[90:91], 0
	v_add_u32_e32 v125, s0, v102
	v_readlane_b32 s0, v253, 21
	v_mov_b32_e32 v139, v86
	v_mov_b32_e32 v140, v41
	v_add_u32_e32 v127, s0, v101
	v_readlane_b32 s0, v253, 22
	v_mov_b32_e32 v141, v61
	s_nop 0
	v_add_u32_e32 v131, s0, v102
	v_readlane_b32 s0, v253, 23
	s_nop 1
	v_add_u32_e32 v134, s0, v101
	s_branch .LBB0_277

; template <int L, int N, int NB> DEVQ void hyena_item(const Params& P, LAS unsigned char* lds, bf16* pT, float* zs, int d, size_t m0, const cf* specd, const float* cornerd) {
;     ...
;                 sconv8(pg, t0, L, w0, w1, w2, bs, ga); sconv8(pg + L, t0, L, w0, w1, w2, bs, gb);
;                 const f32x4 xa0 = *(const f32x4*)(zb + t0), xa1 = *(const f32x4*)(zb + t0 + 4), xb0 = *(const f32x4*)(zb + L + t0), xb1 = *(const f32x4*)(zb + L + t0 + 4);
; #pragma unroll
;                 for (int e = 0; e < 8; ++e) { const cf y = Xb[NB * swz(t0 + e)]; ya[e] = y.x; yb[e] = y.y; }
;                 if (t0 < 16 || t0 + 7 > N / 2) {
; #pragma unroll
;                     for (int e = 0; e < 8; ++e) { const int t = t0 + e;
;                         if (t > N / 2) { const int n1 = t - N / 2 - 1; for (int s = 0; s <= n1; ++s) { const float c = cf1[n1 - s]; ya[e] += c * cxb[s]; yb[e] += c * cxb[32 + s]; } }
;                         if (t < 16) { for (int k = 0; k <= 15 - t; ++k) { const float c = cf2[k]; ya[e] += c * cxb[16 + t + k]; yb[e] += c * cxb[48 + t + k]; } } } }
.LBB0_285:
	s_or_b64 exec, exec, s[6:7]
	v_lshlrev_b64 v[0:1], 2, v[54:55]
	v_lshl_add_u64 v[58:59], s[10:11], 0, v[0:1]
	v_lshl_add_u64 v[56:57], s[12:13], 0, v[0:1]
	flat_load_dwordx4 v[32:35], v[58:59]
	flat_load_dwordx4 v[24:27], v[58:59] offset:16
	flat_load_dwordx4 v[28:31], v[56:57]
	flat_load_dwordx4 v[20:23], v[56:57] offset:16
	v_and_b32_e32 v0, 28, v141
	v_bfe_u32 v1, v141, 2, 2
	v_bitop3_b32 v2, v1, v54, v0 bitop3:0x36
	v_lshlrev_b32_e32 v2, 4, v2
	v_or_b32_e32 v152, 1, v54
	v_add_u32_e32 v142, 0, v2
	v_bitop3_b32 v2, v1, v152, v0 bitop3:0x36
	v_lshlrev_b32_e32 v2, 4, v2
	v_or_b32_e32 v151, 2, v54
	v_add_u32_e32 v143, 0, v2
	v_bitop3_b32 v2, v1, v151, v0 bitop3:0x36
	v_lshlrev_b32_e32 v2, 4, v2
	v_or_b32_e32 v150, 3, v54
	v_add_u32_e32 v144, 0, v2
	v_bitop3_b32 v2, v1, v150, v0 bitop3:0x36
	v_lshlrev_b32_e32 v2, 4, v2
	v_or_b32_e32 v68, 4, v54
	v_add_u32_e32 v145, 0, v2
	v_bitop3_b32 v2, v1, v68, v0 bitop3:0x36
	v_lshlrev_b32_e32 v2, 4, v2
	v_or_b32_e32 v66, 5, v54
	v_add_u32_e32 v146, 0, v2
	v_bitop3_b32 v2, v1, v66, v0 bitop3:0x36
	v_lshlrev_b32_e32 v2, 4, v2
	v_or_b32_e32 v64, 6, v54
	v_or_b32_e32 v62, 7, v54
	v_add_u32_e32 v147, 0, v2
	v_bitop3_b32 v2, v1, v64, v0 bitop3:0x36
	v_bitop3_b32 v0, v1, v62, v0 bitop3:0x36
	v_lshlrev_b32_e32 v2, 4, v2
	v_lshlrev_b32_e32 v0, 4, v0
	ds_read_b64 v[8:9], v142
	ds_read_b64 v[78:79], v143
	ds_read_b64 v[10:11], v144
	ds_read_b64 v[80:81], v145
	v_add_u32_e32 v148, 0, v2
	v_add_u32_e32 v149, 0, v0
	ds_read_b64 v[12:13], v146
	ds_read_b64 v[82:83], v147
	ds_read_b64 v[14:15], v148
	ds_read_b64 v[84:85], v149
	v_cmp_gt_i32_e64 s[0:1], 2, v141
	v_cmp_lt_i32_e64 s[6:7], s50, v62
	s_waitcnt lgkmcnt(0)
	v_mov_b32_e32 v0, v8
	v_mov_b32_e32 v1, v78
	v_mov_b32_e32 v2, v10
	v_mov_b32_e32 v3, v80
	v_mov_b32_e32 v4, v12
	v_mov_b32_e32 v5, v82
	v_mov_b32_e32 v6, v14
	v_mov_b32_e32 v7, v84
	v_mov_b32_e32 v76, v9
	v_mov_b32_e32 v77, v79
	v_mov_b32_e32 v74, v11
	v_mov_b32_e32 v75, v81
	v_mov_b32_e32 v72, v13
	v_mov_b32_e32 v73, v83
	v_mov_b32_e32 v70, v15
	v_mov_b32_e32 v71, v85
	v_cmp_lt_i32_e32 vcc, 1, v141
	s_or_b64 s[8:9], s[0:1], s[6:7]
	s_and_saveexec_b64 s[92:93], s[8:9]
	s_cbranch_execz .LBB0_351
	v_and_b32_e32 v8, 1, v141
	v_cmp_lt_i32_e64 s[94:95], 1, v141
	v_lshlrev_b32_e32 v8, 5, v8
	s_mov_b32 s28, 0x20800
	s_nop 0
	v_cndmask_b32_e64 v9, 0, 64, s[94:95]
	v_add3_u32 v8, v8, v9, s28
	ds_read_b128 v[0:3], v8
	ds_read_b128 v[4:7], v8 offset:16
	ds_read_b128 v[12:15], v8 offset:144
	ds_read_b128 v[8:11], v8 offset:128
	s_waitcnt lgkmcnt(0)
	v_mov_b32_e32 v76, v8
	v_mov_b32_e32 v77, v9
	v_mov_b32_e32 v74, v10
	v_mov_b32_e32 v75, v11
	v_mov_b32_e32 v72, v12
	v_mov_b32_e32 v73, v13
	v_mov_b32_e32 v70, v14
	v_mov_b32_e32 v71, v15

; template <int L, int N, int NB> DEVQ void hyena_item(const Params& P, LAS unsigned char* lds, bf16* pT, float* zs, int d, size_t m0, const cf* specd, const float* cornerd) {
;     ...
;                 sconv8(pg, t0, L, w0, w1, w2, bs, ga); sconv8(pg + L, t0, L, w0, w1, w2, bs, gb);
;                 const f32x4 xa0 = *(const f32x4*)(zb + t0), xa1 = *(const f32x4*)(zb + t0 + 4), xb0 = *(const f32x4*)(zb + L + t0), xb1 = *(const f32x4*)(zb + L + t0 + 4);
; #pragma unroll
;                 for (int e = 0; e < 8; ++e) { const cf y = Xb[NB * swz(t0 + e)]; ya[e] = y.x; yb[e] = y.y; }
;                 if (t0 < 16 || t0 + 7 > N / 2) {
; #pragma unroll
;                     for (int e = 0; e < 8; ++e) { const int t = t0 + e;
;                         if (t > N / 2) { const int n1 = t - N / 2 - 1; for (int s = 0; s <= n1; ++s) { const float c = cf1[n1 - s]; ya[e] += c * cxb[s]; yb[e] += c * cxb[32 + s]; } }
;                         if (t < 16) { for (int k = 0; k <= 15 - t; ++k) { const float c = cf2[k]; ya[e] += c * cxb[16 + t + k]; yb[e] += c * cxb[48 + t + k]; } } } }
.LBB0_369:
	s_or_b64 exec, exec, s[4:5]
	v_lshlrev_b64 v[0:1], 2, v[54:55]
	v_lshl_add_u64 v[58:59], s[14:15], 0, v[0:1]
	v_lshl_add_u64 v[56:57], s[20:21], 0, v[0:1]
	flat_load_dwordx4 v[32:35], v[58:59]
	flat_load_dwordx4 v[24:27], v[58:59] offset:16
	flat_load_dwordx4 v[28:31], v[56:57]
	flat_load_dwordx4 v[20:23], v[56:57] offset:16
	v_and_b32_e32 v0, 28, v118
	v_bfe_u32 v1, v118, 2, 2
	v_bitop3_b32 v2, v1, v54, v0 bitop3:0x36
	v_lshlrev_b32_e32 v2, 4, v2
	v_or_b32_e32 v131, 1, v54
	v_add_u32_e32 v119, 0, v2
	v_bitop3_b32 v2, v1, v131, v0 bitop3:0x36
	v_lshlrev_b32_e32 v2, 4, v2
	v_or_b32_e32 v128, 2, v54
	v_add_u32_e32 v120, 0, v2
	v_bitop3_b32 v2, v1, v128, v0 bitop3:0x36
	v_lshlrev_b32_e32 v2, 4, v2
	v_or_b32_e32 v127, 3, v54
	v_add_u32_e32 v121, 0, v2
	v_bitop3_b32 v2, v1, v127, v0 bitop3:0x36
	v_lshlrev_b32_e32 v2, 4, v2
	v_or_b32_e32 v68, 4, v54
	v_add_u32_e32 v122, 0, v2
	v_bitop3_b32 v2, v1, v68, v0 bitop3:0x36
	v_lshlrev_b32_e32 v2, 4, v2
	v_or_b32_e32 v66, 5, v54
	v_add_u32_e32 v123, 0, v2
	v_bitop3_b32 v2, v1, v66, v0 bitop3:0x36
	v_lshlrev_b32_e32 v2, 4, v2
	v_or_b32_e32 v64, 6, v54
	v_or_b32_e32 v62, 7, v54
	v_add_u32_e32 v124, 0, v2
	v_bitop3_b32 v2, v1, v64, v0 bitop3:0x36
	v_bitop3_b32 v0, v1, v62, v0 bitop3:0x36
	v_lshlrev_b32_e32 v2, 4, v2
	v_lshlrev_b32_e32 v0, 4, v0
	ds_read_b64 v[8:9], v119 offset:8
	ds_read_b64 v[78:79], v120 offset:8
	ds_read_b64 v[10:11], v121 offset:8
	ds_read_b64 v[80:81], v122 offset:8
	v_add_u32_e32 v125, 0, v2
	v_add_u32_e32 v126, 0, v0
	ds_read_b64 v[12:13], v123 offset:8
	ds_read_b64 v[82:83], v124 offset:8
	ds_read_b64 v[14:15], v125 offset:8
	ds_read_b64 v[84:85], v126 offset:8
	v_cmp_gt_i32_e64 s[0:1], 2, v118
	v_cmp_lt_i32_e64 s[4:5], s50, v62
	s_waitcnt lgkmcnt(0)
	v_mov_b32_e32 v0, v8
	v_mov_b32_e32 v1, v78
	v_mov_b32_e32 v2, v10
	v_mov_b32_e32 v3, v80
	v_mov_b32_e32 v4, v12
	v_mov_b32_e32 v5, v82
	v_mov_b32_e32 v6, v14
	v_mov_b32_e32 v7, v84
	v_mov_b32_e32 v76, v9
	v_mov_b32_e32 v77, v79
	v_mov_b32_e32 v74, v11
	v_mov_b32_e32 v75, v81
	v_mov_b32_e32 v72, v13
	v_mov_b32_e32 v73, v83
	v_mov_b32_e32 v70, v15
	v_mov_b32_e32 v71, v85
	v_cmp_lt_i32_e32 vcc, 1, v118
	s_or_b64 s[6:7], s[0:1], s[4:5]
	s_and_saveexec_b64 s[90:91], s[6:7]
	s_cbranch_execz .LBB0_435
	v_and_b32_e32 v8, 1, v118
	v_cmp_lt_i32_e64 s[92:93], 1, v118
	v_lshlrev_b32_e32 v8, 5, v8
	s_mov_b32 s28, 0x20900
	s_nop 0
	v_cndmask_b32_e64 v9, 0, 64, s[92:93]
	v_add3_u32 v8, v8, v9, s28
	ds_read_b128 v[0:3], v8
	ds_read_b128 v[4:7], v8 offset:16
	ds_read_b128 v[12:15], v8 offset:144
	ds_read_b128 v[8:11], v8 offset:128
	s_waitcnt lgkmcnt(0)
	v_mov_b32_e32 v76, v8
	v_mov_b32_e32 v77, v9
	v_mov_b32_e32 v74, v10
	v_mov_b32_e32 v75, v11
	v_mov_b32_e32 v72, v12
	v_mov_b32_e32 v73, v13
	v_mov_b32_e32 v70, v14
	v_mov_b32_e32 v71, v15

; #define LAS __attribute__((address_space(3)))
; template <int L, int N, int NB> DEVQ void hyena_item(const Params& P, LAS unsigned char* lds, bf16* pT, float* zs, int d, size_t m0, const cf* specd, const float* cornerd) {
;     ...
;         const float skv = P.in[17][o * 1024 + d];
;         const int gc = (o + 1) * 1024 + d;
;         const float w0 = cw[gc], w1 = cw[3072 + gc], w2 = cw[6144 + gc], bs = cb[gc];
;         const LAS float* cf1 = cfs + 32 * o; const LAS float* cf2 = cf1 + 16;
; #pragma unroll
;         for (int nb = 0; nb < NB; ++nb) {
;             bf16* pv = pT + (size_t)d * TPAD + m0 + (size_t)nb * 2 * L; const bf16* pg = pT + (size_t)gc * TPAD + m0 + (size_t)nb * 2 * L;
;             float* zb = zs + nb * 2 * L; LAS cf* Xb = X + nb; const LAS float* cxb = cx + 64 * nb;
; #pragma unroll 1
;             for (int q = tid; q < NG; q += NTHR) { const int t0 = 8 * q;
;                 float ga[8], gb[8], ya[8], yb[8];
;                 sconv8(pg, t0, L, w0, w1, w2, bs, ga); sconv8(pg + L, t0, L, w0, w1, w2, bs, gb);
;                 const f32x4 xa0 = *(const f32x4*)(zb + t0), xa1 = *(const f32x4*)(zb + t0 + 4), xb0 = *(const f32x4*)(zb + L + t0), xb1 = *(const f32x4*)(zb + L + t0 + 4);
; #pragma unroll
;                 for (int e = 0; e < 8; ++e) { const cf y = Xb[NB * swz(t0 + e)]; ya[e] = y.x; yb[e] = y.y; }
;                 if (t0 < 16 || t0 + 7 > N / 2) {
; #pragma unroll
;                     for (int e = 0; e < 8; ++e) { const int t = t0 + e;
;                         if (t > N / 2) { const int n1 = t - N / 2 - 1; for (int s = 0; s <= n1; ++s) { const float c = cf1[n1 - s]; ya[e] += c * cxb[s]; yb[e] += c * cxb[32 + s]; } }
;                         if (t < 16) { for (int k = 0; k <= 15 - t; ++k) { const float c = cf2[k]; ya[e] += c * cxb[16 + t + k]; yb[e] += c * cxb[48 + t + k]; } } } }
.LBB0_494:
	s_or_b64 exec, exec, s[0:1]
	s_movk_i32 s0, 0x402
	v_cmp_gt_i32_e32 vcc, s0, v41
	s_waitcnt lgkmcnt(0)
	s_barrier
	s_and_saveexec_b64 s[6:7], vcc
	s_movk_i32 s55, 0x200
	s_cbranch_execz .LBB0_575
	s_lshl_b32 s4, s78, 10
	s_add_i32 s0, s13, s4
	s_ashr_i32 s1, s0, 31
	s_lshl_b32 s5, s78, 7
	s_mul_i32 s3, s0, 0x28400
	s_mul_hi_i32 s2, s0, 0x28400
	s_add_u32 s3, s68, s3
	s_addc_u32 s2, s69, s2
	s_add_u32 s36, s3, 0x20200
	s_addc_u32 s37, s2, 0
	s_add_u32 s72, s3, 0x24220
	s_addc_u32 s73, s2, 0
	s_lshl_b64 s[0:1], s[0:1], 2
	s_add_u32 s2, s67, s0
	s_addc_u32 s3, s66, s1
	s_add_u32 s0, s27, s0
	s_addc_u32 s1, s25, s1
	v_mov_b32_e32 v2, s0
	v_mov_b64_e32 v[4:5], s[0:1]
	s_add_i32 s0, s4, s12
	v_mov_b64_e32 v[0:1], s[2:3]
	v_mov_b32_e32 v3, s1
	s_movk_i32 s2, 0x6000
	s_ashr_i32 s1, s0, 31
	flat_load_dword v42, v[0:1]
	v_add_co_u32_e32 v0, vcc, s2, v2
	s_lshl_b64 s[0:1], s[0:1], 2
	s_nop 0
	v_addc_co_u32_e32 v1, vcc, 0, v3, vcc
	s_add_u32 s0, s17, s0
	v_add_co_u32_e32 v2, vcc, s53, v2
	s_addc_u32 s1, s16, s1
	s_nop 0
	v_addc_co_u32_e32 v3, vcc, 0, v3, vcc
	flat_load_dword v44, v[0:1]
	flat_load_dword v46, v[2:3]
	flat_load_dword v48, v[4:5]
	v_mov_b64_e32 v[0:1], s[0:1]
	flat_load_dword v50, v[0:1]
	v_readfirstlane_b32 s28, v41
	s_lshl_b32 s3, s78, 7
	s_nop 3
	s_cmp_lt_u32 s28, 64
	s_cbranch_scc0 .Lfixpre_skip_ls
	v_and_b32_e32 v0, 31, v41
	v_bfe_u32 v1, v41, 5, 1
	v_cmp_gt_u32_e64 s[82:83], 16, v0
	v_add_u32_e32 v2, -16, v0
	v_sub_u32_e32 v3, 16, v0
	v_add_u32_e32 v4, 16, v0
	v_lshlrev_b32_e32 v5, 2, v2
	v_cndmask_b32_e64 v3, v2, v3, s[82:83]
	v_cndmask_b32_e64 v4, 0, v4, s[82:83]
	v_add_u32_e32 v5, -4, v5
	v_lshl_add_u32 v4, v1, 5, v4
	v_cndmask_b32_e64 v5, v5, 64, s[82:83]
	v_lshlrev_b32_e32 v4, 2, v4
	v_add_u32_e32 v5, s3, v5
	v_add_u32_e32 v4, 0x20000, v4
	v_add_u32_e32 v5, 0x20100, v5
	v_cndmask_b32_e64 v6, -4, 4, s[82:83]
	v_add_u32_e32 v7, 0x2000, v2
	v_cndmask_b32_e64 v7, v7, v0, s[82:83]
	v_lshlrev_b32_e32 v7, 3, v7
	v_lshl_add_u32 v7, v1, 2, v7
	v_lshl_add_u32 v1, v41, 2, 0
	v_add_u32_e32 v1, 0x20800, v1
	v_mad_i32_i24 v0, v6, 0, v5
	ds_read_b32 v24, v0
	v_mad_i32_i24 v0, v6, 1, v5
	ds_read_b32 v25, v0
	v_mad_i32_i24 v0, v6, 2, v5
	ds_read_b32 v26, v0
	v_mad_i32_i24 v0, v6, 3, v5
	ds_read_b32 v27, v0
	v_mad_i32_i24 v0, v6, 4, v5
	ds_read_b32 v28, v0
	v_mad_i32_i24 v0, v6, 5, v5
	ds_read_b32 v29, v0
	v_mad_i32_i24 v0, v6, 6, v5
	ds_read_b32 v30, v0
	v_mad_i32_i24 v0, v6, 7, v5
	ds_read_b32 v31, v0
	v_mad_i32_i24 v0, v6, 8, v5
	ds_read_b32 v32, v0
	v_mad_i32_i24 v0, v6, 9, v5
	ds_read_b32 v33, v0
	v_mad_i32_i24 v0, v6, 10, v5
	ds_read_b32 v34, v0
	v_mad_i32_i24 v0, v6, 11, v5
	ds_read_b32 v35, v0
	v_mad_i32_i24 v0, v6, 12, v5
	ds_read_b32 v36, v0
	v_mad_i32_i24 v0, v6, 13, v5
	ds_read_b32 v37, v0
	v_mad_i32_i24 v0, v6, 14, v5
	ds_read_b32 v38, v0
	v_mad_i32_i24 v0, v6, 15, v5
	ds_read_b32 v39, v0
	ds_read_b32 v2, v7
	ds_read_b32 v8, v4
	ds_read_b32 v9, v4 offset:4
	ds_read_b32 v10, v4 offset:8
	ds_read_b32 v11, v4 offset:12
	ds_read_b32 v12, v4 offset:16
	ds_read_b32 v13, v4 offset:20
	ds_read_b32 v14, v4 offset:24
	ds_read_b32 v15, v4 offset:28
	ds_read_b32 v16, v4 offset:32
	ds_read_b32 v17, v4 offset:36
	ds_read_b32 v18, v4 offset:40
	ds_read_b32 v19, v4 offset:44
	ds_read_b32 v20, v4 offset:48
	ds_read_b32 v21, v4 offset:52
	ds_read_b32 v22, v4 offset:56
	ds_read_b32 v23, v4 offset:60
	s_waitcnt lgkmcnt(0)
	v_cmpx_gt_u32_e64 s[80:81], v3, 0
	v_fmac_f32_e32 v2, v24, v8
	v_cmpx_gt_u32_e64 s[80:81], v3, 1
	v_fmac_f32_e32 v2, v25, v9
	v_cmpx_gt_u32_e64 s[80:81], v3, 2
	v_fmac_f32_e32 v2, v26, v10
	v_cmpx_gt_u32_e64 s[80:81], v3, 3
	v_fmac_f32_e32 v2, v27, v11
	v_cmpx_gt_u32_e64 s[80:81], v3, 4
	v_fmac_f32_e32 v2, v28, v12
	v_cmpx_gt_u32_e64 s[80:81], v3, 5
	v_fmac_f32_e32 v2, v29, v13
	v_cmpx_gt_u32_e64 s[80:81], v3, 6
	v_fmac_f32_e32 v2, v30, v14
	v_cmpx_gt_u32_e64 s[80:81], v3, 7
	v_fmac_f32_e32 v2, v31, v15
	v_cmpx_gt_u32_e64 s[80:81], v3, 8
	v_fmac_f32_e32 v2, v32, v16
	v_cmpx_gt_u32_e64 s[80:81], v3, 9
	v_fmac_f32_e32 v2, v33, v17
	v_cmpx_gt_u32_e64 s[80:81], v3, 10
	v_fmac_f32_e32 v2, v34, v18
	v_cmpx_gt_u32_e64 s[80:81], v3, 11
	v_fmac_f32_e32 v2, v35, v19
	v_cmpx_gt_u32_e64 s[80:81], v3, 12
	v_fmac_f32_e32 v2, v36, v20
	v_cmpx_gt_u32_e64 s[80:81], v3, 13
	v_fmac_f32_e32 v2, v37, v21
	v_cmpx_gt_u32_e64 s[80:81], v3, 14
	v_fmac_f32_e32 v2, v38, v22
	v_cmpx_gt_u32_e64 s[80:81], v3, 15
	v_fmac_f32_e32 v2, v39, v23
	s_mov_b64 exec, -1
	ds_write_b32 v1, v2
	s_waitcnt lgkmcnt(0)
.Lfixpre_skip_ls:
	v_lshlrev_b32_e32 v1, 5, v41
	v_readlane_b32 s0, v254, 37
	v_add_u32_e32 v2, s5, v1
	v_lshlrev_b32_e32 v0, 3, v41
	v_add_u32_e32 v86, s0, v1
	v_readlane_b32 s0, v253, 12
	s_add_i32 s2, s5, 0
	s_mov_b64 s[76:77], 0
	v_add_u32_e32 v88, s0, v1
	v_readlane_b32 s0, v253, 14
	v_add_u32_e32 v84, 0xffffe000, v0
	v_sub_u32_e32 v85, 15, v0
	v_add_u32_e32 v91, s0, v1
	v_readlane_b32 s0, v253, 16
	v_add_u32_e32 v87, 0xffffe001, v0
	v_sub_u32_e32 v89, 14, v0
	v_add_u32_e32 v94, s0, v1
	v_readlane_b32 s0, v254, 38
	v_add_u32_e32 v90, 0xffffe002, v0
	v_sub_u32_e32 v92, 13, v0
	v_add_u32_e32 v97, s0, v1
	v_readlane_b32 s0, v253, 19
	v_add_u32_e32 v93, 0xffffe003, v0
	v_sub_u32_e32 v95, 12, v0
	v_add_u32_e32 v100, s0, v1
	v_readlane_b32 s0, v253, 21
	v_add_u32_e32 v96, 0xffffe004, v0
	v_sub_u32_e32 v98, 11, v0
	v_add_u32_e32 v103, s0, v1
	v_readlane_b32 s0, v253, 23
	v_add_u32_e32 v99, 0xffffe005, v0
	v_sub_u32_e32 v101, 10, v0
	v_add_u32_e32 v106, s0, v1
	v_readlane_b32 s0, v253, 33
	v_add_u32_e32 v102, 0xffffe006, v0
	v_sub_u32_e32 v104, 9, v0
	v_add_u32_e32 v108, s0, v2
	v_readlane_b32 s0, v253, 34
	v_add_u32_e32 v105, 0xffffe007, v0
	v_sub_u32_e32 v107, 8, v0
	v_add_u32_e32 v109, s0, v2
	v_readlane_b32 s0, v253, 35
	s_add_i32 s2, s2, 0x20140
	v_mov_b32_e32 v116, v41
	v_add_u32_e32 v110, s0, v2
	v_readlane_b32 s0, v253, 36
	s_waitcnt vmcnt(0) lgkmcnt(0)
	v_mov_b32_e32 v43, v42
	v_add_u32_e32 v111, s0, v2
	v_readlane_b32 s0, v253, 37
	v_mov_b32_e32 v45, v44
	s_nop 0
	v_add_u32_e32 v112, s0, v2
	v_readlane_b32 s0, v253, 38
	v_mov_b32_e32 v49, v48
	v_mov_b32_e32 v47, v46
	v_add_u32_e32 v113, s0, v2
	v_readlane_b32 s0, v253, 39
	v_mov_b32_e32 v52, v46
	v_mov_b32_e32 v53, v48
	v_add_u32_e32 v114, s0, v2
	v_readlane_b32 s0, v253, 40
	v_mov_b32_e32 v51, v50
	s_nop 0
	v_add_u32_e32 v115, s0, v2
	s_branch .LBB0_497

; template <int L, int N, int NB> DEVQ void hyena_item(const Params& P, LAS unsigned char* lds, bf16* pT, float* zs, int d, size_t m0, const cf* specd, const float* cornerd) {
;     ...
;                 sconv8(pg, t0, L, w0, w1, w2, bs, ga); sconv8(pg + L, t0, L, w0, w1, w2, bs, gb);
;                 const f32x4 xa0 = *(const f32x4*)(zb + t0), xa1 = *(const f32x4*)(zb + t0 + 4), xb0 = *(const f32x4*)(zb + L + t0), xb1 = *(const f32x4*)(zb + L + t0 + 4);
; #pragma unroll
;                 for (int e = 0; e < 8; ++e) { const cf y = Xb[NB * swz(t0 + e)]; ya[e] = y.x; yb[e] = y.y; }
;                 if (t0 < 16 || t0 + 7 > N / 2) {
; #pragma unroll
;                     for (int e = 0; e < 8; ++e) { const int t = t0 + e;
;                         if (t > N / 2) { const int n1 = t - N / 2 - 1; for (int s = 0; s <= n1; ++s) { const float c = cf1[n1 - s]; ya[e] += c * cxb[s]; yb[e] += c * cxb[32 + s]; } }
;                         if (t < 16) { for (int k = 0; k <= 15 - t; ++k) { const float c = cf2[k]; ya[e] += c * cxb[16 + t + k]; yb[e] += c * cxb[48 + t + k]; } } } }
.LBB0_505:
	s_or_b64 exec, exec, s[4:5]
	v_lshlrev_b64 v[0:1], 2, v[54:55]
	v_lshl_add_u64 v[58:59], s[10:11], 0, v[0:1]
	v_lshl_add_u64 v[56:57], s[8:9], 0, v[0:1]
	flat_load_dwordx4 v[32:35], v[58:59]
	flat_load_dwordx4 v[24:27], v[58:59] offset:16
	flat_load_dwordx4 v[28:31], v[56:57]
	flat_load_dwordx4 v[20:23], v[56:57] offset:16
	v_and_b32_e32 v0, 28, v116
	v_bfe_u32 v1, v116, 2, 2
	v_bitop3_b32 v2, v1, v54, v0 bitop3:0x36
	v_or_b32_e32 v127, 1, v54
	v_lshl_add_u32 v117, v2, 3, 0
	v_bitop3_b32 v2, v1, v127, v0 bitop3:0x36
	v_or_b32_e32 v126, 2, v54
	v_lshl_add_u32 v118, v2, 3, 0
	v_bitop3_b32 v2, v1, v126, v0 bitop3:0x36
	v_or_b32_e32 v125, 3, v54
	v_lshl_add_u32 v119, v2, 3, 0
	v_bitop3_b32 v2, v1, v125, v0 bitop3:0x36
	v_or_b32_e32 v66, 4, v54
	v_lshl_add_u32 v120, v2, 3, 0
	v_bitop3_b32 v2, v1, v66, v0 bitop3:0x36
	v_or_b32_e32 v64, 5, v54
	v_lshl_add_u32 v121, v2, 3, 0
	v_bitop3_b32 v2, v1, v64, v0 bitop3:0x36
	v_or_b32_e32 v62, 6, v54
	v_or_b32_e32 v60, 7, v54
	v_lshl_add_u32 v122, v2, 3, 0
	v_bitop3_b32 v2, v1, v62, v0 bitop3:0x36
	v_bitop3_b32 v0, v1, v60, v0 bitop3:0x36
	ds_read_b64 v[8:9], v117
	ds_read_b64 v[76:77], v118
	ds_read_b64 v[10:11], v119
	ds_read_b64 v[78:79], v120
	v_lshl_add_u32 v123, v2, 3, 0
	v_lshl_add_u32 v124, v0, 3, 0
	ds_read_b64 v[12:13], v121
	ds_read_b64 v[80:81], v122
	ds_read_b64 v[14:15], v123
	ds_read_b64 v[82:83], v124
	v_cmp_gt_i32_e64 s[0:1], 2, v116
	v_cmp_lt_i32_e32 vcc, s47, v60
	s_waitcnt lgkmcnt(0)
	v_mov_b32_e32 v0, v8
	v_mov_b32_e32 v1, v76
	v_mov_b32_e32 v2, v10
	v_mov_b32_e32 v3, v78
	v_mov_b32_e32 v4, v12
	v_mov_b32_e32 v5, v80
	v_mov_b32_e32 v6, v14
	v_mov_b32_e32 v7, v82
	v_mov_b32_e32 v74, v9
	v_mov_b32_e32 v75, v77
	v_mov_b32_e32 v72, v11
	v_mov_b32_e32 v73, v79
	v_mov_b32_e32 v70, v13
	v_mov_b32_e32 v71, v81
	v_mov_b32_e32 v68, v15
	v_mov_b32_e32 v69, v83
	s_or_b64 s[4:5], s[0:1], vcc
	s_and_saveexec_b64 s[78:79], s[4:5]
	s_cbranch_execz .LBB0_571
	v_and_b32_e32 v8, 1, v116
	v_cmp_lt_i32_e64 s[80:81], 1, v116
	v_lshlrev_b32_e32 v8, 5, v8
	s_mov_b32 s28, 0x20800
	s_nop 0
	v_cndmask_b32_e64 v9, 0, 64, s[80:81]
	v_add3_u32 v8, v8, v9, s28
	ds_read_b128 v[0:3], v8
	ds_read_b128 v[4:7], v8 offset:16
	ds_read_b128 v[12:15], v8 offset:144
	ds_read_b128 v[8:11], v8 offset:128
	s_waitcnt lgkmcnt(0)
	v_mov_b32_e32 v74, v8
	v_mov_b32_e32 v75, v9
	v_mov_b32_e32 v72, v10
	v_mov_b32_e32 v73, v11
	v_mov_b32_e32 v70, v12
	v_mov_b32_e32 v71, v13
	v_mov_b32_e32 v68, v14
	v_mov_b32_e32 v69, v15
